# stack + row sum-of-squares of the next proj tile prefetched one tile ahead (no exposed load wait at epilogue start)
# speedup vs baseline: 1.0211x; 1.0049x over previous
; #define PG8_STAGE(bufoff, gbase, voff) do { _Pragma("unroll") for (int _i = 0; _i < 2; ++_i) \
;         __builtin_amdgcn_global_load_lds((const unsigned*)((const char*)(gbase) + (voff)[_i]), (LAS unsigned*)(lds + (bufoff) + ldsw + _i * 8192), 16, 0, 0); } while (0)
; #define PG8_BAR __builtin_amdgcn_s_barrier()
; template <class Epi, class Order = StaticOrder, bool HALFN = false>
; __device__ __forceinline__ void gemm_phase(LAS unsigned char* lds, const Gemm g, const Epi& E) {
;     ...
;     for (int i = 0; i < 2; ++i) { int R, C; stage_rc(tid * 16 + i * 8192, R, C); const int Rb = (R & ~31) + perm32(R & 31);
;         voffA[i] = (unsigned)(R * g.lda + C) * 2u; voffB[i] = (unsigned)(Rb * g.ldb + C) * 2u; }
;     const size_t kstep = (size_t)(BK * 2);
;     const size_t hstepA = (size_t)HALF * g.lda * 2, hstepB = (size_t)HALF * g.ldb * 2;
;     const size_t tstepA = 2 * hstepA, tstepB = 2 * hstepB;
;     const unsigned ldsw = (unsigned)wid * 1024u;
;     const int aoff = lds_byte(wr * 64 + fr, fq * 8), boff = lds_byte(wc * 32 + fr, fq * 8);
;     ...
;     Unit cur, nxt; int ui = 0;
;     if (!S.next(0, cur)) return;
;     f32x4 acc[2][2][4][2];
;     if constexpr (Epi::INIT) E.init(acc, cur, wr, wc, fr, fq);
;     else {
; #pragma unroll
;     for (int a = 0; a < 2; ++a)
; #pragma unroll
;         for (int b = 0; b < 2; ++b)
; #pragma unroll
;             for (int m = 0; m < 4; ++m)
; #pragma unroll
;                 for (int n = 0; n < 2; ++n) acc[a][b][m][n] = (f32x4){0.f, 0.f, 0.f, 0.f};
;     }
;     bf16x8 At[4][2], B0[2][2], B1[2][2];
;     const char* cA = (const char*)g.A + (size_t)cur.pm * tstepA + (size_t)cur.pn * g.a_pn_off * 2; const char* cB = (const char*)g.Bt + (size_t)cur.pn * tstepB + (HALFN ? (size_t)(cur.half - 1) * hstepB : (size_t)0);
;     PG8_STAGE(PG8_SB(0, 0), cB, voffB); PG8_STAGE(PG8_SB(0, 1), cB + hstepB, voffB); PG8_STAGE(PG8_SA(0, 0), cA, voffA); PG8_STAGE(PG8_SA(0, 1), cA + hstepA, voffA);
;     if (wr == 1) PG8_BAR;
;     __device__ __forceinline__ void operator()(f32x4 (&acc)[2][2][4][2], const Unit& u, int wr, int wc, int fr, int fq) const {
;     ...
;             for (int m = 0; m < 4; ++m) rsv[ai][m] = ssq[u.pm * 256 + ai * 128 + wr * 64 + m * 16 + fr];
.LBB0_180:
	s_mul_i32 s6, s78, 0x3c00000
	v_readlane_b32 s7, v252, 36
	s_add_u32 s10, s7, s6
	v_readlane_b32 s6, v252, 37
	s_addc_u32 s11, s6, 0
	s_lshl_b32 s56, s78, 13
	v_readlane_b32 s16, v251, 39
	s_lshl_b64 s[6:7], s[56:57], 2
	v_readlane_b32 s18, v251, 41
	v_readlane_b32 s19, v251, 42
	s_add_u32 s44, s18, s6
	s_addc_u32 s45, s19, s7
	s_andn2_b64 vcc, exec, s[4:5]
	v_readlane_b32 s17, v251, 40
	s_cbranch_vccnz .LBB0_225
	s_lshr_b32 s98, s8, 2
	s_and_b32 s98, s98, 64
	s_lshl_b32 s99, s94, 8
	s_add_i32 s98, s98, s99
	v_and_b32_e32 v2, 15, v10
	v_add_u32_e32 v2, s98, v2
	v_ashrrev_i32_e32 v3, 31, v2
	v_lshl_add_u64 v[2:3], v[2:3], 2, s[44:45]
	global_load_dword v194, v[2:3], off
	global_load_dword v195, v[2:3], off offset:64
	global_load_dword v196, v[2:3], off offset:128
	global_load_dword v197, v[2:3], off offset:192
	global_load_dword v198, v[2:3], off offset:512
	global_load_dword v199, v[2:3], off offset:576
	global_load_dword v200, v[2:3], off offset:640
	global_load_dword v201, v[2:3], off offset:704
	v_ashrrev_i32_e32 v2, 31, v10
	v_lshrrev_b32_e32 v2, 26, v2
	v_add_u32_e32 v2, v10, v2
	v_ashrrev_i32_e32 v11, 6, v2
	v_bfe_i32 v2, v10, 27, 1
	v_lshlrev_b32_e32 v1, 4, v10
	v_lshrrev_b32_e32 v2, 22, v2
	v_add_u32_e32 v2, v1, v2
	v_and_b32_e32 v2, 0xfffffc00, v2
	v_sub_u32_e32 v2, v1, v2
	s_waitcnt lgkmcnt(0)
	v_lshrrev_b32_e32 v3, 4, v2
	v_bitop3_b32 v2, v3, v2, 32 bitop3:0x6c
	v_ashrrev_i32_e32 v4, 31, v2
	v_lshrrev_b32_e32 v4, 26, v4
	v_add_u32_e32 v4, v2, v4
	v_lshlrev_b32_e32 v3, 3, v11
	v_ashrrev_i32_e32 v12, 6, v4
	v_and_b32_e32 v4, 0xc0, v4
	v_and_b32_e32 v3, -16, v3
	v_sub_u32_e32 v2, v2, v4
	v_add_u32_e32 v3, v12, v3
	v_ashrrev_i16_sdwa v2, v190, sext(v2) dst_sel:DWORD dst_unused:UNUSED_PAD src0_sel:DWORD src1_sel:BYTE_0
	v_lshlrev_b32_e32 v5, 5, v11
	v_bfe_i32 v13, v2, 0, 16
	v_lshlrev_b32_e32 v2, 1, v3
	v_lshrrev_b32_e32 v4, 2, v3
	v_and_b32_e32 v6, 3, v12
	s_mov_b32 s4, 0xfffe0
	v_and_b32_e32 v5, 32, v5
	v_and_b32_e32 v2, 24, v2
	v_and_b32_e32 v4, 4, v4
	v_and_or_b32 v6, v3, s4, v6
	v_or3_b32 v2, v6, v4, v2
	v_add_lshl_u32 v4, v5, v13, 1
	v_add_u32_e32 v1, 0x2000, v1
	v_lshl_add_u32 v132, v2, 12, v4
	v_ashrrev_i32_e32 v2, 31, v1
	v_lshrrev_b32_e32 v2, 22, v2
	v_add_u32_e32 v2, v1, v2
	v_ashrrev_i32_e32 v14, 10, v2
	v_mul_i32_i24_e32 v2, 0x400, v14
	v_sub_u32_e32 v1, v1, v2
	v_lshrrev_b32_e32 v2, 4, v1
	v_bitop3_b32 v1, v2, v1, 32 bitop3:0x6c
	v_lshl_add_u32 v130, v3, 12, v4
	v_ashrrev_i32_e32 v3, 31, v1
	v_lshrrev_b32_e32 v3, 26, v3
	v_lshlrev_b32_e32 v2, 3, v14
	v_add_u32_e32 v3, v1, v3
	v_and_b32_e32 v2, -16, v2
	v_ashrrev_i32_e32 v15, 6, v3
	v_add_u32_e32 v2, v15, v2
	v_and_b32_e32 v3, 0xc0, v3
	v_and_b32_e32 v5, 3, v15
	s_ashr_i32 s7, s8, 6
	s_ashr_i32 s95, s94, 31
	s_ashr_i32 s53, s52, 31
	s_ashr_i32 s6, s8, 8
	v_sub_u32_e32 v1, v1, v3
	v_and_or_b32 v5, v2, s4, v5
	s_lshl_b32 s56, s7, 10
	s_lshl_b64 s[16:17], s[94:95], 20
	s_lshl_b64 s[4:5], s[52:53], 20
	v_ashrrev_i16_sdwa v1, v190, sext(v1) dst_sel:DWORD dst_unused:UNUSED_PAD src0_sel:DWORD src1_sel:BYTE_0
	s_add_u32 s4, s10, s4
	v_lshlrev_b32_e32 v4, 5, v14
	v_bfe_i32 v16, v1, 0, 16
	v_lshlrev_b32_e32 v1, 1, v2
	v_lshrrev_b32_e32 v3, 2, v2
	s_addc_u32 s5, s11, s5
	s_add_i32 s53, s56, 0
	v_and_b32_e32 v4, 32, v4
	v_and_b32_e32 v1, 24, v1
	v_and_b32_e32 v3, 4, v3
	s_add_i32 m0, s53, 0x10000
	v_or3_b32 v1, v5, v3, v1
	v_add_lshl_u32 v3, v4, v16, 1
	global_load_lds_dwordx4 v132, s[4:5]
	s_add_i32 m0, s53, 0x12000
	v_lshl_add_u32 v136, v1, 12, v3
	s_add_u32 s18, s4, 0x80000
	global_load_lds_dwordx4 v136, s[4:5]
	s_addc_u32 s19, s5, 0
	s_add_i32 m0, s53, 0x14000
	v_lshl_add_u32 v134, v2, 12, v3
	global_load_lds_dwordx4 v132, s[18:19]
	s_add_i32 m0, s53, 0x16000
	s_add_u32 s62, s0, s16
	s_addc_u32 s63, s1, s17
	s_add_i32 s80, s53, 0x2000
	global_load_lds_dwordx4 v136, s[18:19]
	s_mov_b32 m0, s53
	s_add_u32 s16, s62, 0x80000
	global_load_lds_dwordx4 v130, s[62:63]
	s_mov_b32 m0, s80
	s_addc_u32 s17, s63, 0
	s_add_i32 s81, s53, 0x4000
	global_load_lds_dwordx4 v134, s[62:63]
	s_mov_b32 m0, s81
	s_add_i32 s82, s53, 0x6000
	global_load_lds_dwordx4 v130, s[16:17]
	s_mov_b32 m0, s82
	v_mov_b32_e32 v133, v0
	global_load_lds_dwordx4 v134, s[16:17]
	v_mov_b32_e32 v137, v0
	v_mov_b32_e32 v131, v0
	v_mov_b32_e32 v135, v0
	s_cmp_eq_u32 s6, 1
	v_lshl_add_u64 v[8:9], s[4:5], 0, v[132:133]
	v_lshl_add_u64 v[6:7], s[4:5], 0, v[136:137]
	v_lshl_add_u64 v[2:3], s[62:63], 0, v[130:131]
	s_cselect_b64 s[40:41], -1, 0
	s_cmp_lg_u32 s6, 1
	v_lshl_add_u64 v[4:5], s[62:63], 0, v[134:135]
	s_cbranch_scc1 .LBB0_183
	s_barrier

;     __device__ __forceinline__ void operator()(f32x4 (&acc)[2][2][4][2], const Unit& u, int wr, int wc, int fr, int fq) const {
;     ...
;         for (int ai = 0; ai < 2; ++ai)
; #pragma unroll
;             for (int m = 0; m < 4; ++m) rsv[ai][m] = ssq[u.pm * 256 + ai * 128 + wr * 64 + m * 16 + fr];
;         asm volatile("" ::: "memory");
; #pragma unroll
;         for (int ai = 0; ai < 2; ++ai)
; #pragma unroll
;             for (int m = 0; m < 4; ++m) rsv[ai][m] = __builtin_amdgcn_rsqf(rsv[ai][m] * (1.0f / DM) + RMS_EPS);
;         const int pn = u.pn + pn0;
.LBB0_197:
	s_lshl_b32 s4, s94, 8
	v_mov_b32_e32 v142, v1
	v_mov_b32_e32 v210, v143
	s_add_i32 s4, s4, s83
	s_cmp_gt_i32 s52, 7
	v_add_u32_e32 v154, s4, v142
	v_ashrrev_i32_e32 v155, 31, v154
	v_add_u32_e32 v209, 16, v154
	v_add_u32_e32 v208, 32, v154
	v_add_u32_e32 v157, 48, v154
	v_add_u32_e32 v155, 0x80, v154
	v_add_u32_e32 v153, 0x90, v154
	v_add_u32_e32 v151, 0xa0, v154
	v_add_u32_e32 v149, 0xb0, v154
	s_mov_b64 s[4:5], -1
	v_fmamk_f32 v142, v194, 0x3a000000, v189
	v_fmamk_f32 v144, v195, 0x3a000000, v189
	v_fmamk_f32 v146, v196, 0x3a000000, v189
	v_fmamk_f32 v150, v197, 0x3a000000, v189
	v_fmamk_f32 v159, v198, 0x3a000000, v189
	v_fmamk_f32 v160, v199, 0x3a000000, v189
	v_fmamk_f32 v161, v200, 0x3a000000, v189
	v_fmamk_f32 v168, v201, 0x3a000000, v189
	v_rsq_f32_e32 v158, v142
	v_rsq_f32_e32 v156, v144
	v_rsq_f32_e32 v152, v146
	v_rsq_f32_e32 v150, v150
	v_rsq_f32_e32 v148, v159
	v_rsq_f32_e32 v146, v160
	v_rsq_f32_e32 v144, v161
	v_rsq_f32_e32 v142, v168
	v_lshl_add_u32 v168, s48, 8, v1
	v_add_u32_e32 v168, s83, v168
	v_ashrrev_i32_e32 v169, 31, v168
	v_lshl_add_u64 v[168:169], v[168:169], 2, s[44:45]
	global_load_dword v194, v[168:169], off
	global_load_dword v195, v[168:169], off offset:64
	global_load_dword v196, v[168:169], off offset:128
	global_load_dword v197, v[168:169], off offset:192
	global_load_dword v198, v[168:169], off offset:512
	global_load_dword v199, v[168:169], off offset:576
	global_load_dword v200, v[168:169], off offset:640
	global_load_dword v201, v[168:169], off offset:704
	s_cbranch_scc1 .LBB0_200
	s_andn2_b64 vcc, exec, s[4:5]
	s_cbranch_vccz .LBB0_221

; #define PG8_WAIT_V(n) asm volatile("s_waitcnt vmcnt(" #n ")" ::: "memory")
; #define PG8_BAR __builtin_amdgcn_s_barrier()
; template <class Epi, class Order = StaticOrder, bool HALFN = false>
; __device__ __forceinline__ void gemm_phase(LAS unsigned char* lds, const Gemm g, const Epi& E) {
;     ...
;     PG8_WAIT_V(0);
;     PG8_BAR;
.LBB0_224:
	v_mov_b32_e32 v194, 0x3e000000
	v_mov_b32_e32 v195, 0x3eaaaaab
	v_mov_b32_e32 v196, 0x3e800000
	v_mov_b32_e32 v197, 0x3e4ccccd
	v_mov_b32_e32 v198, 0x3e2aaaab
	v_mov_b32_e32 v199, 0x3e124925
	v_mov_b32_e32 v200, 0x3d800000
	v_mov_b32_e32 v201, 0x3de38e39
	s_waitcnt vmcnt(0)
	s_barrier
